# v41 + one static s_setprio 1 for waves 0-3 (older half) during the attention phase (reset at phase exit)
# speedup vs baseline: 1.0030x; 1.0008x over previous
; #define REP(k) for (int rep_ = 0; rep_ < (((DUP_MASK >> (k)) & 1u) ? 2 : 1); ++rep_)
; __global__ void __launch_bounds__(NWAVES * 64, 2) mk_fwd(Args args) {
;     ...
;     if (IN(3)) REP(3) {
;         for (int idx = vcu; idx < 512; idx += G) {
;             const int bh = idx >> 3, qb = idx & 7, b = bh >> 4, h = bh & 15;
;             const size_t row0 = (size_t)b * SEQ + qb * 256, key0 = (size_t)b * SEQ;
;             att::attn_unit(QB + row0 * 3072 + h * 192, KVB + key0 * 4096 + h * 256, KVB + key0 * 4096 + h * 256 + 128, KPE + key0 * 64, AO + row0 * 2048 + h * 128, SEQ, (att::lptr)lds, wave);
.LBB0_446:
	v_readlane_b32 vcc_lo, v237, 2
	s_nop 0
	s_cmp_lt_u32 vcc_lo, 4
	s_cbranch_scc0 .Lattn_prio_skip
	s_setprio 1
